# v17 + split-phase grid barrier after scan: non-leader workgroups defer the generation wait + acquire until before retc's first state load (stages 0-2 overlap the barrier)
# speedup vs baseline: 1.0044x; 1.0044x over previous
; __device__ __forceinline__ unsigned xb_add(unsigned* p, unsigned v) { return __hip_atomic_fetch_add(p, v, __ATOMIC_RELAXED, __HIP_MEMORY_SCOPE_AGENT); }
; __device__ __forceinline__ void xcd_barrier(const int wv, const XcdBarrier& b) {
;     asm volatile("s_waitcnt vmcnt(0)" ::: "memory");
;     __syncthreads();
;     if (TIDX == 0) {
;         unsigned long long barq = (unsigned long long)b.bar; asm volatile("" : "+s"(barq));
;         unsigned* bar = (unsigned*)barq;
;         __builtin_amdgcn_s_waitcnt(0);
;         unsigned nloc = b.st[0], nx = b.st[1];
;         if (nloc == 0u) { xcd_barrier_complete(bar, b.x, nloc, nx); b.st[0] = nloc; b.st[1] = nx; }
;         const unsigned old = xb_add(&bar[XB_XSUB(b.x)], 1u);
.LBB0_422:
	s_or_b64 exec, exec, s[0:1]
	s_mov_b32 s101, 0
	s_waitcnt vmcnt(0)
	s_barrier
	v_mbcnt_lo_u32_b32 v1, -1, 0
	v_mbcnt_hi_u32_b32 v1, -1, v1
	s_nop 0
	v_sub_u32_e32 v1, 0, v1
	v_cmp_eq_u32_e32 vcc, s53, v1
	s_and_saveexec_b64 s[0:1], vcc
	s_cbranch_execz .LBB0_466
	s_mov_b64 s[2:3], s[58:59]
	v_mov_b32_e32 v1, s73
	s_waitcnt vmcnt(0) expcnt(0) lgkmcnt(0)
	ds_read_b32 v6, v1
	v_mov_b32_e32 v1, s74
	ds_read_b32 v4, v1
	s_waitcnt lgkmcnt(1)
	v_cmp_ne_u32_e32 vcc, 0, v6
	s_cbranch_vccnz .LBB0_437
	s_add_u32 s4, s2, 0x1000
	s_addc_u32 s5, s3, 0
	s_add_u32 s6, s2, 0x1100
	s_addc_u32 s7, s3, 0
	s_add_u32 s8, s2, 0x1200
	s_addc_u32 s9, s3, 0
	s_add_u32 s10, s2, 0x1300
	s_addc_u32 s11, s3, 0
	s_mov_b32 s30, 1
	s_mov_b64 s[12:13], 0
	s_branch .LBB0_427

; __device__ __forceinline__ unsigned xb_ld(unsigned* p)              { return __hip_atomic_load(p, __ATOMIC_RELAXED, __HIP_MEMORY_SCOPE_AGENT); }
; __device__ __forceinline__ unsigned xb_add(unsigned* p, unsigned v) { return __hip_atomic_fetch_add(p, v, __ATOMIC_RELAXED, __HIP_MEMORY_SCOPE_AGENT); }
; #define XB_SPIN(cond, bar) do { unsigned _sp = 0; while (cond) { __builtin_amdgcn_s_sleep(1); \
;     if ((++_sp & 255u) == 0u) { if (xb_ld(&(bar)[XB_TMO])) break; if (_sp > XB_SPIN_CAP) { atomicAdd(&(bar)[XB_TMO], 1u); break; } } } } while (0)
; __device__ __forceinline__ void xcd_barrier(const int wv, const XcdBarrier& b) {
;     ...
;         if (nloc == 0u) { xcd_barrier_complete(bar, b.x, nloc, nx); b.st[0] = nloc; b.st[1] = nx; }
;         const unsigned old = xb_add(&bar[XB_XSUB(b.x)], 1u);
;         const unsigned gen = old / nloc;
;         if (old + 1u == (gen + 1u) * nloc) {
;             __builtin_amdgcn_fence(__ATOMIC_RELEASE, "agent");
;             asm volatile("s_waitcnt vmcnt(0)" ::: "memory");
;             const unsigned og = xb_add(&bar[XB_TOP], 1u);
;             const unsigned tg = og / nx;
;             if (og + 1u == (tg + 1u) * nx) xb_add(&bar[XB_TOPGEN], 1u);
;             else XB_SPIN(xb_ld(&bar[XB_TOPGEN]) == tg, bar);
;             __builtin_amdgcn_fence(__ATOMIC_ACQUIRE, "agent");
;             xb_add(&bar[XB_XGEN(b.x)], 1u);
;             asm volatile("s_waitcnt vmcnt(0)" ::: "memory");
;         } else {
;             XB_SPIN(xb_ld(&bar[XB_XGEN(b.x)]) == gen, bar);
;             __builtin_amdgcn_fence(__ATOMIC_ACQUIRE, "agent");
;             asm volatile("s_waitcnt vmcnt(0)" ::: "memory");
;         }
.LBB0_437:
	v_lshl_add_u64 v[2:3], v[178:179], 2, s[2:3]
	v_add_co_u32_e32 v8, vcc, 0x1000, v2
	v_cvt_f32_u32_e32 v1, v6
	s_nop 0
	v_addc_co_u32_e32 v9, vcc, 0, v3, vcc
	flat_atomic_add v5, v[8:9], v184 offset:1024 sc0
	v_rcp_iflag_f32_e32 v1, v1
	v_sub_u32_e32 v7, 0, v6
	v_mul_f32_e32 v1, 0x4f7ffffe, v1
	v_cvt_u32_f32_e32 v1, v1
	v_mul_lo_u32 v7, v7, v1
	v_mul_hi_u32 v7, v1, v7
	v_add_u32_e32 v1, v1, v7
	s_waitcnt vmcnt(0) lgkmcnt(0)
	v_mul_hi_u32 v1, v5, v1
	v_mul_lo_u32 v7, v1, v6
	v_sub_u32_e32 v7, v5, v7
	v_cmp_ge_u32_e32 vcc, v7, v6
	v_add_u32_e32 v8, 1, v1
	v_add_u32_e32 v5, 1, v5
	v_cndmask_b32_e32 v1, v1, v8, vcc
	v_sub_u32_e32 v8, v7, v6
	v_cndmask_b32_e32 v7, v7, v8, vcc
	v_cmp_ge_u32_e32 vcc, v7, v6
	v_add_u32_e32 v7, 1, v1
	s_nop 0
	v_cndmask_b32_e32 v1, v1, v7, vcc
	v_mad_u64_u32 v[6:7], s[4:5], v6, v1, v[6:7]
	v_cmp_ne_u32_e32 vcc, v5, v6
	s_and_saveexec_b64 s[4:5], vcc
	s_xor_b64 s[4:5], exec, s[4:5]
	s_cbranch_execz .LBB0_450
	v_add_co_u32_e32 v4, vcc, 0x2400, v2
	s_nop 1
	v_addc_co_u32_e32 v5, vcc, 0, v3, vcc
	s_nop 0
	v_readfirstlane_b32 s98, v4
	v_readfirstlane_b32 s99, v5
	v_readfirstlane_b32 s100, v1
	s_mov_b32 s101, 0x40000

; #define WAITV0() asm volatile("s_waitcnt vmcnt(0)" ::: "memory")
; #define LBAR() do { asm volatile("s_waitcnt lgkmcnt(0)" ::: "memory"); __builtin_amdgcn_s_barrier(); asm volatile("" ::: "memory"); } while (0)
; __device__ __forceinline__ unsigned xb_ld(unsigned* p)              { return __hip_atomic_load(p, __ATOMIC_RELAXED, __HIP_MEMORY_SCOPE_AGENT); }
; #define XB_SPIN(cond, bar) do { unsigned _sp = 0; while (cond) { __builtin_amdgcn_s_sleep(1); \
;     if ((++_sp & 255u) == 0u) { if (xb_ld(&(bar)[XB_TMO])) break; if (_sp > XB_SPIN_CAP) { atomicAdd(&(bar)[XB_TMO], 1u); break; } } } } while (0)
; __device__ __forceinline__ void retc_stream(const int wv, LAS unsigned char* lds, unsigned ldsb, const float* __restrict__ gn_g, const float* __restrict__ gn_b, const bf16_t* __restrict__ qkvr, const bf16_t* __restrict__ grb, const bf16_t* __restrict__ kv, ...
;     ...
;         for (int vh = 0; vh < 2; ++vh) {
;             WAITV0(); LBAR(); RETC_ISSUE(item, 3 + vh);
; __device__ __forceinline__ void xcd_barrier(const int wv, const XcdBarrier& b) {
;     ...
;             XB_SPIN(xb_ld(&bar[XB_XGEN(b.x)]) == gen, bar);
;             __builtin_amdgcn_fence(__ATOMIC_ACQUIRE, "agent");
;             asm volatile("s_waitcnt vmcnt(0)" ::: "memory");
.LBB0_492:
	s_cmp_eq_u32 s101, 0
	s_cbranch_scc1 .Lgw_done
	v_mov_b32_e32 v222, s98
	v_mov_b32_e32 v223, s99
.Lgw_spin:
	global_load_dword v224, v[222:223], off sc1
	s_waitcnt vmcnt(0)
	v_cmp_ne_u32_e32 vcc, s100, v224
	s_cbranch_vccnz .Lgw_got
	s_sleep 1
	s_sub_u32 s101, s101, 1
	s_cmp_lg_u32 s101, 0
	s_cbranch_scc1 .Lgw_spin
.Lgw_got:
	buffer_inv sc1
	s_waitcnt vmcnt(0)
	s_mov_b32 s101, 0

; __global__ void __launch_bounds__(512, 2) mega(Params p_unused) {
	.amdhsa_kernel _Z4mega6Params
		.amdhsa_group_segment_fixed_size 0
		.amdhsa_private_segment_fixed_size 0
		.amdhsa_kernarg_size 376
		.amdhsa_user_sgpr_count 2
		.amdhsa_user_sgpr_dispatch_ptr 0
		.amdhsa_user_sgpr_queue_ptr 0
		.amdhsa_user_sgpr_kernarg_segment_ptr 1
		.amdhsa_user_sgpr_dispatch_id 0
		.amdhsa_user_sgpr_kernarg_preload_length 0
		.amdhsa_user_sgpr_kernarg_preload_offset 0
		.amdhsa_user_sgpr_private_segment_size 0
		.amdhsa_uses_dynamic_stack 0
		.amdhsa_enable_private_segment 0
		.amdhsa_system_sgpr_workgroup_id_x 1
		.amdhsa_system_sgpr_workgroup_id_y 0
		.amdhsa_system_sgpr_workgroup_id_z 0
		.amdhsa_system_sgpr_workgroup_info 0
		.amdhsa_system_vgpr_workitem_id 2
		.amdhsa_next_free_vgpr 255
		.amdhsa_next_free_sgpr 102
		.amdhsa_accum_offset 256
		.amdhsa_reserve_vcc 1
		.amdhsa_float_round_mode_32 0
		.amdhsa_float_round_mode_16_64 0
		.amdhsa_float_denorm_mode_32 3
		.amdhsa_float_denorm_mode_16_64 3
		.amdhsa_dx10_clamp 1
		.amdhsa_ieee_mode 1
		.amdhsa_fp16_overflow 0
		.amdhsa_tg_split 0
		.amdhsa_exception_fp_ieee_invalid_op 0
		.amdhsa_exception_fp_denorm_src 0
		.amdhsa_exception_fp_ieee_div_zero 0
		.amdhsa_exception_fp_ieee_overflow 0
		.amdhsa_exception_fp_ieee_underflow 0
		.amdhsa_exception_fp_ieee_inexact 0
		.amdhsa_exception_int_div_zero 0
	.end_amdhsa_kernel

; __global__ void __launch_bounds__(512, 2) mega(Params p_unused) {
amdhsa.kernels:
  - .agpr_count:     0
    .args:
      - .offset:         0
        .size:           120
        .value_kind:     by_value
      - .offset:         120
        .size:           4
        .value_kind:     hidden_block_count_x
      - .offset:         124
        .size:           4
        .value_kind:     hidden_block_count_y
      - .offset:         128
        .size:           4
        .value_kind:     hidden_block_count_z
      - .offset:         132
        .size:           2
        .value_kind:     hidden_group_size_x
      - .offset:         134
        .size:           2
        .value_kind:     hidden_group_size_y
      - .offset:         136
        .size:           2
        .value_kind:     hidden_group_size_z
      - .offset:         138
        .size:           2
        .value_kind:     hidden_remainder_x
      - .offset:         140
        .size:           2
        .value_kind:     hidden_remainder_y
      - .offset:         142
        .size:           2
        .value_kind:     hidden_remainder_z
      - .offset:         160
        .size:           8
        .value_kind:     hidden_global_offset_x
      - .offset:         168
        .size:           8
        .value_kind:     hidden_global_offset_y
      - .offset:         176
        .size:           8
        .value_kind:     hidden_global_offset_z
      - .offset:         184
        .size:           2
        .value_kind:     hidden_grid_dims
      - .offset:         208
        .size:           8
        .value_kind:     hidden_multigrid_sync_arg
      - .offset:         240
        .size:           4
        .value_kind:     hidden_dynamic_lds_size
    .group_segment_fixed_size: 0
    .kernarg_segment_align: 8
    .kernarg_segment_size: 376
    .language:       OpenCL C
    .language_version:
      - 2
      - 0
    .max_flat_workgroup_size: 512
    .name:           _Z4mega6Params
    .private_segment_fixed_size: 0
    .sgpr_count:     108
    .sgpr_spill_count: 203
    .symbol:         _Z4mega6Params.kd
    .uniform_work_group_size: 1
    .uses_dynamic_stack: false
    .vgpr_count:     255
    .vgpr_spill_count: 0
    .wavefront_size: 64
